# v17: near-tile table reads as ds_read2_b32 pairs
# speedup vs baseline: 1.0160x; 1.0032x over previous
.LBB0_634:
	s_lshl_b32 s0, 1, s0
	s_waitcnt vmcnt(0)
	v_and_b32_e32 v0, s0, v187
	v_and_b32_e32 v66, s0, v188
	v_cmp_ne_u32_e64 s[6:7], 0, v0
	v_cmp_ne_u32_e32 vcc, 0, v66
	v_cmp_le_u32_e64 s[8:9], s85, v143
	v_cmp_le_u32_e64 s[2:3], s85, v177
	s_and_b64 s[8:9], s[8:9], s[6:7]
	s_and_b64 s[2:3], s[2:3], vcc
	s_cmp_lg_u64 s[8:9], 0
	s_cselect_b64 s[8:9], -1, 0
	s_cmp_lg_u64 s[2:3], 0
	s_cselect_b64 s[2:3], -1, 0
	v_cndmask_b32_e64 v0, 0, 1, s[8:9]
	v_cndmask_b32_e64 v167, 0, 1, s[2:3]
	s_or_b64 s[0:1], s[8:9], s[2:3]
	s_and_saveexec_b64 s[54:55], s[0:1]
	s_cbranch_execz .LBB0_646
	s_cmp_eq_u32 s87, 0
	s_cselect_b64 s[58:59], -1, 0
	s_and_b64 s[0:1], s[58:59], exec
	s_cselect_b32 s0, 0, 0x2400
	v_add_u32_e32 v168, s0, v178
	ds_read_b128 v[158:161], v168
	ds_read_b128 v[162:165], v176 offset:53248
	v_cmp_gt_i32_e64 s[4:5], s85, v190
	s_waitcnt lgkmcnt(2)
	v_cndmask_b32_e64 v66, v173, v189, s[6:7]
	ds_read_b128 v[196:199], v168 offset:32
	ds_read_b128 v[202:205], v176 offset:54272
	ds_read_b128 v[206:209], v176 offset:57344
	ds_read_b128 v[210:213], v176 offset:58368
	v_cndmask_b32_e64 v166, 0, v171, s[4:5]
	v_cndmask_b32_e64 v66, v66, 0, s[4:5]
	v_cndmask_b32_e32 v67, v173, v189, vcc
	v_cmp_gt_i32_e64 s[4:5], s85, v191
	v_cndmask_b32_e64 v240, v173, v66, s[8:9]
	s_nop 0
	v_cndmask_b32_e64 v67, v67, 0, s[4:5]
	s_nop 1
	v_cndmask_b32_e64 v241, v173, v67, s[2:3]
	s_waitcnt lgkmcnt(4)
	v_mfma_f32_32x32x16_bf16 v[98:113], v[158:161], v[162:165], 0
	s_waitcnt lgkmcnt(1)
	v_mfma_f32_32x32x16_bf16 v[114:129], v[158:161], v[206:209], 0
	ds_read_b128 v[158:161], v168 offset:4608
	ds_read_b128 v[214:217], v168 offset:4640
	s_waitcnt lgkmcnt(1)
	v_mfma_f32_32x32x16_bf16 v[82:97], v[158:161], v[162:165], 0
	v_mfma_f32_32x32x16_bf16 v[66:81], v[158:161], v[206:209], 0
	v_mfma_f32_32x32x16_bf16 v[98:113], v[196:199], v[202:205], v[98:113]
	v_mfma_f32_32x32x16_bf16 v[114:129], v[196:199], v[210:213], v[114:129]
	ds_read_b128 v[158:161], v168 offset:64
	ds_read_b128 v[162:165], v176 offset:55296
	ds_read_b128 v[196:199], v168 offset:96
	ds_read_b128 v[206:209], v176 offset:56320
	s_waitcnt lgkmcnt(4)
	v_mfma_f32_32x32x16_bf16 v[82:97], v[214:217], v[202:205], v[82:97]
	v_mfma_f32_32x32x16_bf16 v[66:81], v[214:217], v[210:213], v[66:81]
	ds_read_b128 v[202:205], v176 offset:59392
	ds_read_b128 v[210:213], v176 offset:60416
	s_waitcnt lgkmcnt(4)
	v_mfma_f32_32x32x16_bf16 v[98:113], v[158:161], v[162:165], v[98:113]
	s_waitcnt lgkmcnt(1)
	v_mfma_f32_32x32x16_bf16 v[114:129], v[158:161], v[202:205], v[114:129]
	ds_read_b128 v[158:161], v168 offset:4672
	ds_read_b128 v[214:217], v168 offset:4704
	s_waitcnt lgkmcnt(1)
	v_mfma_f32_32x32x16_bf16 v[82:97], v[158:161], v[162:165], v[82:97]
	v_mfma_f32_32x32x16_bf16 v[66:81], v[158:161], v[202:205], v[66:81]
	v_cndmask_b32_e64 v158, 0, v172, s[6:7]
	v_or3_b32 v0, v158, v166, v0
	v_cndmask_b32_e64 v158, v158, v0, s[8:9]
	v_and_b32_e32 v0, 0x100, v158
	v_cmp_ne_u32_e64 s[6:7], 0, v0
	v_add_u32_e32 v0, s60, v192
	v_mfma_f32_32x32x16_bf16 v[98:113], v[196:199], v[206:209], v[98:113]
	v_mfma_f32_32x32x16_bf16 v[114:129], v[196:199], v[210:213], v[114:129]
	s_waitcnt lgkmcnt(0)
	v_mfma_f32_32x32x16_bf16 v[82:97], v[214:217], v[206:209], v[82:97]
	v_mfma_f32_32x32x16_bf16 v[66:81], v[214:217], v[210:213], v[66:81]
	s_and_saveexec_b64 s[8:9], s[6:7]
	s_cbranch_execz .LBB0_641
	v_lshl_add_u32 v206, v0, 2, s92
	v_and_b32_e32 v205, 0x10000, v158
	v_cmp_ne_u32_e64 s[6:7], 0, v205
	v_mov_b32_e32 v207, s93
	s_nop 1
	v_cndmask_b32_e64 v206, v207, v206, s[6:7]
	ds_read2_b32 v[208:209], v206 offset0:59 offset1:58
	ds_read2_b32 v[210:211], v206 offset0:57 offset1:56
	ds_read2_b32 v[212:213], v206 offset0:51 offset1:50
	ds_read2_b32 v[214:215], v206 offset0:49 offset1:48
	ds_read2_b32 v[216:217], v206 offset0:43 offset1:42
	ds_read2_b32 v[218:219], v206 offset0:41 offset1:40
	ds_read2_b32 v[220:221], v206 offset0:35 offset1:34
	ds_read2_b32 v[222:223], v206 offset0:33 offset1:32
	ds_read2_b32 v[224:225], v206 offset0:27 offset1:26
	ds_read2_b32 v[226:227], v206 offset0:25 offset1:24
	ds_read2_b32 v[228:229], v206 offset0:19 offset1:18
	ds_read2_b32 v[230:231], v206 offset0:17 offset1:16
	ds_read2_b32 v[232:233], v206 offset0:11 offset1:10
	ds_read2_b32 v[234:235], v206 offset0:9 offset1:8
	ds_read2_b32 v[236:237], v206 offset0:3 offset1:2
	ds_read2_b32 v[238:239], v206 offset0:1 offset1:0
	s_waitcnt lgkmcnt(8)
	v_pk_add_f32 v[98:99], v[98:99], v[208:209]
	v_pk_add_f32 v[100:101], v[100:101], v[210:211]
	v_pk_add_f32 v[102:103], v[102:103], v[212:213]
	v_pk_add_f32 v[104:105], v[104:105], v[214:215]
	v_pk_add_f32 v[106:107], v[106:107], v[216:217]
	v_pk_add_f32 v[108:109], v[108:109], v[218:219]
	v_pk_add_f32 v[110:111], v[110:111], v[220:221]
	v_pk_add_f32 v[112:113], v[112:113], v[222:223]
	s_waitcnt lgkmcnt(0)
	v_pk_add_f32 v[82:83], v[82:83], v[224:225]
	v_pk_add_f32 v[84:85], v[84:85], v[226:227]
	v_pk_add_f32 v[86:87], v[86:87], v[228:229]
	v_pk_add_f32 v[88:89], v[88:89], v[230:231]
	v_pk_add_f32 v[90:91], v[90:91], v[232:233]
	v_pk_add_f32 v[92:93], v[92:93], v[234:235]
	v_pk_add_f32 v[94:95], v[94:95], v[236:237]
	v_pk_add_f32 v[96:97], v[96:97], v[238:239]
.LBB0_641:
	s_or_b64 exec, exec, s[8:9]
	v_cndmask_b32_e32 v158, 0, v172, vcc
	v_cndmask_b32_e64 v159, 0, v171, s[4:5]
	v_or3_b32 v159, v158, v159, v167
	v_cndmask_b32_e64 v158, v158, v159, s[2:3]
	v_and_b32_e32 v159, 0x100, v158
	v_cmp_ne_u32_e32 vcc, 0, v159
	s_and_saveexec_b64 s[2:3], vcc
	s_cbranch_execz .LBB0_643
	v_lshl_add_u32 v206, v0, 2, s94
	v_and_b32_e32 v205, 0x10000, v158
	v_cmp_ne_u32_e32 vcc, 0, v205
	v_mov_b32_e32 v207, s93
	s_nop 1
	v_cndmask_b32_e32 v206, v207, v206, vcc
	ds_read2_b32 v[208:209], v206 offset0:59 offset1:58
	ds_read2_b32 v[210:211], v206 offset0:57 offset1:56
	ds_read2_b32 v[212:213], v206 offset0:51 offset1:50
	ds_read2_b32 v[214:215], v206 offset0:49 offset1:48
	ds_read2_b32 v[216:217], v206 offset0:43 offset1:42
	ds_read2_b32 v[218:219], v206 offset0:41 offset1:40
	ds_read2_b32 v[220:221], v206 offset0:35 offset1:34
	ds_read2_b32 v[222:223], v206 offset0:33 offset1:32
	ds_read2_b32 v[224:225], v206 offset0:27 offset1:26
	ds_read2_b32 v[226:227], v206 offset0:25 offset1:24
	ds_read2_b32 v[228:229], v206 offset0:19 offset1:18
	ds_read2_b32 v[230:231], v206 offset0:17 offset1:16
	ds_read2_b32 v[232:233], v206 offset0:11 offset1:10
	ds_read2_b32 v[234:235], v206 offset0:9 offset1:8
	ds_read2_b32 v[236:237], v206 offset0:3 offset1:2
	ds_read2_b32 v[238:239], v206 offset0:1 offset1:0
	s_waitcnt lgkmcnt(8)
	v_pk_add_f32 v[114:115], v[114:115], v[208:209]
	v_pk_add_f32 v[116:117], v[116:117], v[210:211]
	v_pk_add_f32 v[118:119], v[118:119], v[212:213]
	v_pk_add_f32 v[120:121], v[120:121], v[214:215]
	v_pk_add_f32 v[122:123], v[122:123], v[216:217]
	v_pk_add_f32 v[124:125], v[124:125], v[218:219]
	v_pk_add_f32 v[126:127], v[126:127], v[220:221]
	v_pk_add_f32 v[128:129], v[128:129], v[222:223]
	s_waitcnt lgkmcnt(0)
	v_pk_add_f32 v[66:67], v[66:67], v[224:225]
	v_pk_add_f32 v[68:69], v[68:69], v[226:227]
	v_pk_add_f32 v[70:71], v[70:71], v[228:229]
	v_pk_add_f32 v[72:73], v[72:73], v[230:231]
	v_pk_add_f32 v[74:75], v[74:75], v[232:233]
	v_pk_add_f32 v[76:77], v[76:77], v[234:235]
	v_pk_add_f32 v[78:79], v[78:79], v[236:237]
	v_pk_add_f32 v[80:81], v[80:81], v[238:239]

.LBB0_655:
	s_add_i32 s0, s84, 63
	v_cmp_le_u32_e32 vcc, s84, v143
	v_cmp_ge_i32_e64 s[2:3], s0, v168
	s_and_b64 s[2:3], vcc, s[2:3]
	v_cmp_le_u32_e32 vcc, s84, v177
	v_cmp_ge_i32_e64 s[4:5], s0, v169
	s_and_b64 vcc, vcc, s[4:5]
	s_or_b64 s[4:5], s[2:3], vcc
	s_and_saveexec_b64 s[60:61], s[4:5]
	s_cbranch_execz .LBB0_663
	v_cmp_gt_i32_e64 s[4:5], s0, v182
	v_cmp_lt_i32_e64 s[6:7], s84, v183
	v_cmp_gt_i32_e64 s[8:9], s0, v167
	v_cmp_lt_i32_e64 s[10:11], s84, v185
	s_or_b64 s[6:7], s[4:5], s[6:7]
	s_or_b64 s[8:9], s[8:9], s[10:11]
	s_cmp_eq_u32 s86, 0
	s_cselect_b64 s[4:5], -1, 0
	s_and_b64 s[0:1], s[4:5], exec
	s_waitcnt lgkmcnt(0)
	v_cndmask_b32_e64 v0, v184, 0, s[6:7]
	v_cndmask_b32_e64 v66, v184, 0, s[8:9]
	s_cselect_b32 s0, 0, 0x2400
	v_cndmask_b32_e64 v244, v173, v66, s[2:3]
	v_cndmask_b32_e32 v245, v173, v0, vcc
	v_add_u32_e32 v0, s0, v178
	ds_read_b128 v[156:159], v0
	ds_read_b128 v[160:163], v176 offset:53248
	ds_read_b128 v[188:191], v0 offset:32
	ds_read_b128 v[192:195], v176 offset:54272
	ds_read_b128 v[196:199], v176 offset:57344
	ds_read_b128 v[202:205], v176 offset:58368
	s_waitcnt lgkmcnt(4)
	v_mfma_f32_32x32x16_bf16 v[98:113], v[156:159], v[160:163], 0
	s_and_b64 s[0:1], s[2:3], s[8:9]
	s_waitcnt lgkmcnt(1)
	v_mfma_f32_32x32x16_bf16 v[114:129], v[156:159], v[196:199], 0
	ds_read_b128 v[156:159], v0 offset:4608
	ds_read_b128 v[206:209], v0 offset:4640
	s_waitcnt lgkmcnt(1)
	v_mfma_f32_32x32x16_bf16 v[82:97], v[156:159], v[160:163], 0
	v_mfma_f32_32x32x16_bf16 v[66:81], v[156:159], v[196:199], 0
	ds_read_b128 v[156:159], v0 offset:64
	ds_read_b128 v[160:163], v176 offset:55296
	ds_read_b128 v[212:215], v0 offset:96
	ds_read_b128 v[216:219], v176 offset:56320
	v_mfma_f32_32x32x16_bf16 v[98:113], v[188:191], v[192:195], v[98:113]
	v_mfma_f32_32x32x16_bf16 v[114:129], v[188:191], v[202:205], v[114:129]
	ds_read_b128 v[188:191], v176 offset:59392
	ds_read_b128 v[220:223], v176 offset:60416
	s_waitcnt lgkmcnt(6)
	v_mfma_f32_32x32x16_bf16 v[82:97], v[206:209], v[192:195], v[82:97]
	v_mfma_f32_32x32x16_bf16 v[66:81], v[206:209], v[202:205], v[66:81]
	s_waitcnt lgkmcnt(4)
	v_mfma_f32_32x32x16_bf16 v[98:113], v[156:159], v[160:163], v[98:113]
	s_waitcnt lgkmcnt(1)
	v_mfma_f32_32x32x16_bf16 v[114:129], v[156:159], v[188:191], v[114:129]
	ds_read_b128 v[156:159], v0 offset:4672
	ds_read_b128 v[224:227], v0 offset:4704
	s_waitcnt lgkmcnt(1)
	v_mfma_f32_32x32x16_bf16 v[82:97], v[156:159], v[160:163], v[82:97]
	v_mfma_f32_32x32x16_bf16 v[66:81], v[156:159], v[188:191], v[66:81]
	v_mfma_f32_32x32x16_bf16 v[98:113], v[212:215], v[216:219], v[98:113]
	v_mfma_f32_32x32x16_bf16 v[114:129], v[212:215], v[220:223], v[114:129]
	s_waitcnt lgkmcnt(0)
	v_mfma_f32_32x32x16_bf16 v[82:97], v[224:227], v[216:219], v[82:97]
	v_mfma_f32_32x32x16_bf16 v[66:81], v[224:227], v[220:223], v[66:81]
	s_and_saveexec_b64 s[8:9], s[0:1]
	s_cbranch_execz .LBB0_658
	v_lshl_add_u32 v211, v181, 2, s95
	ds_read2_b32 v[212:213], v211 offset0:59 offset1:58
	ds_read2_b32 v[214:215], v211 offset0:57 offset1:56
	ds_read2_b32 v[216:217], v211 offset0:51 offset1:50
	ds_read2_b32 v[218:219], v211 offset0:49 offset1:48
	ds_read2_b32 v[220:221], v211 offset0:43 offset1:42
	ds_read2_b32 v[222:223], v211 offset0:41 offset1:40
	ds_read2_b32 v[224:225], v211 offset0:35 offset1:34
	ds_read2_b32 v[226:227], v211 offset0:33 offset1:32
	ds_read2_b32 v[228:229], v211 offset0:27 offset1:26
	ds_read2_b32 v[230:231], v211 offset0:25 offset1:24
	ds_read2_b32 v[232:233], v211 offset0:19 offset1:18
	ds_read2_b32 v[234:235], v211 offset0:17 offset1:16
	ds_read2_b32 v[236:237], v211 offset0:11 offset1:10
	ds_read2_b32 v[238:239], v211 offset0:9 offset1:8
	ds_read2_b32 v[240:241], v211 offset0:3 offset1:2
	ds_read2_b32 v[242:243], v211 offset0:1 offset1:0
	s_waitcnt lgkmcnt(8)
	v_pk_add_f32 v[98:99], v[98:99], v[212:213]
	v_pk_add_f32 v[100:101], v[100:101], v[214:215]
	v_pk_add_f32 v[102:103], v[102:103], v[216:217]
	v_pk_add_f32 v[104:105], v[104:105], v[218:219]
	v_pk_add_f32 v[106:107], v[106:107], v[220:221]
	v_pk_add_f32 v[108:109], v[108:109], v[222:223]
	v_pk_add_f32 v[110:111], v[110:111], v[224:225]
	v_pk_add_f32 v[112:113], v[112:113], v[226:227]
	s_waitcnt lgkmcnt(0)
	v_pk_add_f32 v[82:83], v[82:83], v[228:229]
	v_pk_add_f32 v[84:85], v[84:85], v[230:231]
	v_pk_add_f32 v[86:87], v[86:87], v[232:233]
	v_pk_add_f32 v[88:89], v[88:89], v[234:235]
	v_pk_add_f32 v[90:91], v[90:91], v[236:237]
	v_pk_add_f32 v[92:93], v[92:93], v[238:239]
	v_pk_add_f32 v[94:95], v[94:95], v[240:241]
	v_pk_add_f32 v[96:97], v[96:97], v[242:243]
.LBB0_658:
	s_or_b64 exec, exec, s[8:9]
	s_and_b64 s[0:1], vcc, s[6:7]
	s_and_saveexec_b64 s[2:3], s[0:1]
	s_cbranch_execz .LBB0_660
	v_lshl_add_u32 v211, v181, 2, s96
	ds_read2_b32 v[212:213], v211 offset0:59 offset1:58
	ds_read2_b32 v[214:215], v211 offset0:57 offset1:56
	ds_read2_b32 v[216:217], v211 offset0:51 offset1:50
	ds_read2_b32 v[218:219], v211 offset0:49 offset1:48
	ds_read2_b32 v[220:221], v211 offset0:43 offset1:42
	ds_read2_b32 v[222:223], v211 offset0:41 offset1:40
	ds_read2_b32 v[224:225], v211 offset0:35 offset1:34
	ds_read2_b32 v[226:227], v211 offset0:33 offset1:32
	ds_read2_b32 v[228:229], v211 offset0:27 offset1:26
	ds_read2_b32 v[230:231], v211 offset0:25 offset1:24
	ds_read2_b32 v[232:233], v211 offset0:19 offset1:18
	ds_read2_b32 v[234:235], v211 offset0:17 offset1:16
	ds_read2_b32 v[236:237], v211 offset0:11 offset1:10
	ds_read2_b32 v[238:239], v211 offset0:9 offset1:8
	ds_read2_b32 v[240:241], v211 offset0:3 offset1:2
	ds_read2_b32 v[242:243], v211 offset0:1 offset1:0
	s_waitcnt lgkmcnt(8)
	v_pk_add_f32 v[114:115], v[114:115], v[212:213]
	v_pk_add_f32 v[116:117], v[116:117], v[214:215]
	v_pk_add_f32 v[118:119], v[118:119], v[216:217]
	v_pk_add_f32 v[120:121], v[120:121], v[218:219]
	v_pk_add_f32 v[122:123], v[122:123], v[220:221]
	v_pk_add_f32 v[124:125], v[124:125], v[222:223]
	v_pk_add_f32 v[126:127], v[126:127], v[224:225]
	v_pk_add_f32 v[128:129], v[128:129], v[226:227]
	s_waitcnt lgkmcnt(0)
	v_pk_add_f32 v[66:67], v[66:67], v[228:229]
	v_pk_add_f32 v[68:69], v[68:69], v[230:231]
	v_pk_add_f32 v[70:71], v[70:71], v[232:233]
	v_pk_add_f32 v[72:73], v[72:73], v[234:235]
	v_pk_add_f32 v[74:75], v[74:75], v[236:237]
	v_pk_add_f32 v[76:77], v[76:77], v[238:239]
	v_pk_add_f32 v[78:79], v[78:79], v[240:241]
	v_pk_add_f32 v[80:81], v[80:81], v[242:243]

.LBB0_1326:
	s_lshr_b32 s0, s0, 2
	s_lshl_b32 s0, 1, s0
	v_and_b32_e32 v64, s0, v205
	v_and_b32_e32 v65, s0, v175
	v_cmp_ne_u32_e64 s[4:5], 0, v64
	v_cmp_ne_u32_e32 vcc, 0, v65
	v_cmp_le_i32_e64 s[6:7], s18, v206
	v_cmp_le_i32_e64 s[2:3], s18, v207
	s_and_b64 s[6:7], s[6:7], s[4:5]
	s_and_b64 s[2:3], s[2:3], vcc
	s_cmp_lg_u64 s[6:7], 0
	s_cselect_b64 s[6:7], -1, 0
	s_cmp_lg_u64 s[2:3], 0
	s_cselect_b64 s[2:3], -1, 0
	v_cndmask_b32_e64 v64, 0, 1, s[6:7]
	v_cndmask_b32_e64 v168, 0, 1, s[2:3]
	s_or_b64 s[0:1], s[6:7], s[2:3]
	s_and_saveexec_b64 s[12:13], s[0:1]
	s_cbranch_execz .LBB0_1338
	v_add_u32_e32 v65, s19, v208
	v_subrev_u32_e32 v66, 63, v65
	v_cmp_gt_i32_e64 s[8:9], s87, v66
	v_cndmask_b32_e64 v215, 0, v202, s[4:5]
	s_cmp_eq_u32 s97, 0
	v_cndmask_b32_e64 v66, 0, v198, s[8:9]
	v_or3_b32 v216, v215, v66, v64
	s_waitcnt lgkmcnt(8)
	v_cndmask_b32_e64 v64, v203, v212, s[4:5]
	v_cndmask_b32_e64 v64, v64, 0, s[8:9]
	s_cselect_b64 s[8:9], -1, 0
	s_and_b64 s[0:1], s[8:9], exec
	s_cselect_b32 s0, 0, 0x2400
	v_subrev_u32_e32 v65, 31, v65
	v_add_u32_e32 v217, s0, v209
	v_cmp_gt_i32_e64 s[4:5], s87, v65
	v_cndmask_b32_e32 v65, v203, v212, vcc
	ds_read_b128 v[186:189], v217 offset:4608
	ds_read_b128 v[190:193], v217
	ds_read_b128 v[194:197], v217 offset:32
	v_cndmask_b32_e64 v65, v65, 0, s[4:5]
	v_cndmask_b32_e64 v252, v203, v64, s[6:7]
	v_cndmask_b32_e64 v253, v203, v65, s[2:3]
	s_waitcnt lgkmcnt(1)
	v_mfma_f32_32x32x16_bf16 v[96:111], v[190:193], v[128:131], 0
	v_mfma_f32_32x32x16_bf16 v[112:127], v[190:193], v[148:151], 0
	v_mfma_f32_32x32x16_bf16 v[80:95], v[186:189], v[128:131], 0
	v_mfma_f32_32x32x16_bf16 v[64:79], v[186:189], v[148:151], 0
	ds_read_b128 v[186:189], v217 offset:4640
	s_waitcnt lgkmcnt(1)
	v_mfma_f32_32x32x16_bf16 v[96:111], v[194:197], v[132:135], v[96:111]
	v_mfma_f32_32x32x16_bf16 v[112:127], v[194:197], v[140:143], v[112:127]
	s_waitcnt lgkmcnt(0)
	v_mfma_f32_32x32x16_bf16 v[80:95], v[186:189], v[132:135], v[80:95]
	v_mfma_f32_32x32x16_bf16 v[64:79], v[186:189], v[140:143], v[64:79]
	ds_read_b128 v[186:189], v217 offset:64
	ds_read_b128 v[190:193], v217 offset:4672
	s_waitcnt lgkmcnt(1)
	v_mfma_f32_32x32x16_bf16 v[96:111], v[186:189], v[136:139], v[96:111]
	v_mfma_f32_32x32x16_bf16 v[112:127], v[186:189], v[144:147], v[112:127]
	s_waitcnt lgkmcnt(0)
	v_mfma_f32_32x32x16_bf16 v[80:95], v[190:193], v[136:139], v[80:95]
	v_mfma_f32_32x32x16_bf16 v[64:79], v[190:193], v[144:147], v[64:79]
	ds_read_b128 v[186:189], v217 offset:96
	ds_read_b128 v[190:193], v217 offset:4704
	s_waitcnt lgkmcnt(1)
	v_mfma_f32_32x32x16_bf16 v[96:111], v[186:189], v[152:155], v[96:111]
	v_mfma_f32_32x32x16_bf16 v[112:127], v[186:189], v[156:159], v[112:127]
	v_cndmask_b32_e64 v186, v215, v216, s[6:7]
	v_and_b32_e32 v187, 0x100, v186
	v_cmp_ne_u32_e64 s[6:7], 0, v187
	s_waitcnt lgkmcnt(0)
	v_mfma_f32_32x32x16_bf16 v[80:95], v[190:193], v[152:155], v[80:95]
	v_mfma_f32_32x32x16_bf16 v[64:79], v[190:193], v[156:159], v[64:79]
	v_add_u32_e32 v190, s19, v211
	s_and_saveexec_b64 s[14:15], s[6:7]
	s_cbranch_execz .LBB0_1333
	v_lshl_add_u32 v224, v190, 2, s91
	v_and_b32_e32 v186, 0x10000, v186
	v_cmp_ne_u32_e64 s[6:7], 0, v186
	v_mov_b32_e32 v225, 0x1d000
	s_nop 1
	v_cndmask_b32_e64 v224, v225, v224, s[6:7]
	ds_read2_b32 v[226:227], v224 offset0:59 offset1:58
	ds_read2_b32 v[228:229], v224 offset0:57 offset1:56
	ds_read2_b32 v[230:231], v224 offset0:51 offset1:50
	ds_read2_b32 v[232:233], v224 offset0:49 offset1:48
	ds_read2_b32 v[234:235], v224 offset0:43 offset1:42
	ds_read2_b32 v[236:237], v224 offset0:41 offset1:40
	ds_read2_b32 v[238:239], v224 offset0:35 offset1:34
	ds_read2_b32 v[240:241], v224 offset0:33 offset1:32
	ds_read2_b32 v[242:243], v224 offset0:27 offset1:26
	ds_read2_b32 v[244:245], v224 offset0:25 offset1:24
	ds_read2_b32 v[246:247], v224 offset0:19 offset1:18
	ds_read2_b32 v[248:249], v224 offset0:17 offset1:16
	ds_read2_b32 v[250:251], v224 offset0:11 offset1:10
	s_waitcnt lgkmcnt(5)
	v_pk_add_f32 v[96:97], v[96:97], v[226:227]
	v_pk_add_f32 v[98:99], v[98:99], v[228:229]
	v_pk_add_f32 v[100:101], v[100:101], v[230:231]
	v_pk_add_f32 v[102:103], v[102:103], v[232:233]
	v_pk_add_f32 v[104:105], v[104:105], v[234:235]
	v_pk_add_f32 v[106:107], v[106:107], v[236:237]
	v_pk_add_f32 v[108:109], v[108:109], v[238:239]
	v_pk_add_f32 v[110:111], v[110:111], v[240:241]
	ds_read2_b32 v[226:227], v224 offset0:9 offset1:8
	ds_read2_b32 v[228:229], v224 offset0:3 offset1:2
	ds_read2_b32 v[230:231], v224 offset0:1 offset1:0
	s_waitcnt lgkmcnt(3)
	v_pk_add_f32 v[80:81], v[80:81], v[242:243]
	v_pk_add_f32 v[82:83], v[82:83], v[244:245]
	v_pk_add_f32 v[84:85], v[84:85], v[246:247]
	v_pk_add_f32 v[86:87], v[86:87], v[248:249]
	v_pk_add_f32 v[88:89], v[88:89], v[250:251]
	s_waitcnt lgkmcnt(0)
	v_pk_add_f32 v[90:91], v[90:91], v[226:227]
	v_pk_add_f32 v[92:93], v[92:93], v[228:229]
	v_pk_add_f32 v[94:95], v[94:95], v[230:231]
.LBB0_1333:
	s_or_b64 exec, exec, s[14:15]
	v_cndmask_b32_e32 v186, 0, v202, vcc
	v_cndmask_b32_e64 v187, 0, v198, s[4:5]
	v_or3_b32 v168, v186, v187, v168
	v_cndmask_b32_e64 v168, v186, v168, s[2:3]
	v_and_b32_e32 v186, 0x100, v168
	v_cmp_ne_u32_e32 vcc, 0, v186
	s_and_saveexec_b64 s[2:3], vcc
	s_cbranch_execz .LBB0_1335
	v_lshl_add_u32 v224, v190, 2, s32
	v_and_b32_e32 v187, 0x10000, v168
	v_cmp_ne_u32_e32 vcc, 0, v187
	v_mov_b32_e32 v225, 0x1d000
	s_nop 1
	v_cndmask_b32_e32 v224, v225, v224, vcc
	ds_read2_b32 v[226:227], v224 offset0:59 offset1:58
	ds_read2_b32 v[228:229], v224 offset0:57 offset1:56
	ds_read2_b32 v[230:231], v224 offset0:51 offset1:50
	ds_read2_b32 v[232:233], v224 offset0:49 offset1:48
	ds_read2_b32 v[234:235], v224 offset0:43 offset1:42
	ds_read2_b32 v[236:237], v224 offset0:41 offset1:40
	ds_read2_b32 v[238:239], v224 offset0:35 offset1:34
	ds_read2_b32 v[240:241], v224 offset0:33 offset1:32
	ds_read2_b32 v[242:243], v224 offset0:27 offset1:26
	ds_read2_b32 v[244:245], v224 offset0:25 offset1:24
	ds_read2_b32 v[246:247], v224 offset0:19 offset1:18
	ds_read2_b32 v[248:249], v224 offset0:17 offset1:16
	ds_read2_b32 v[250:251], v224 offset0:11 offset1:10
	s_waitcnt lgkmcnt(5)
	v_pk_add_f32 v[112:113], v[112:113], v[226:227]
	v_pk_add_f32 v[114:115], v[114:115], v[228:229]
	v_pk_add_f32 v[116:117], v[116:117], v[230:231]
	v_pk_add_f32 v[118:119], v[118:119], v[232:233]
	v_pk_add_f32 v[120:121], v[120:121], v[234:235]
	v_pk_add_f32 v[122:123], v[122:123], v[236:237]
	v_pk_add_f32 v[124:125], v[124:125], v[238:239]
	v_pk_add_f32 v[126:127], v[126:127], v[240:241]
	ds_read2_b32 v[226:227], v224 offset0:9 offset1:8
	ds_read2_b32 v[228:229], v224 offset0:3 offset1:2
	ds_read2_b32 v[230:231], v224 offset0:1 offset1:0
	s_waitcnt lgkmcnt(3)
	v_pk_add_f32 v[64:65], v[64:65], v[242:243]
	v_pk_add_f32 v[66:67], v[66:67], v[244:245]
	v_pk_add_f32 v[68:69], v[68:69], v[246:247]
	v_pk_add_f32 v[70:71], v[70:71], v[248:249]
	v_pk_add_f32 v[72:73], v[72:73], v[250:251]
	s_waitcnt lgkmcnt(0)
	v_pk_add_f32 v[74:75], v[74:75], v[226:227]
	v_pk_add_f32 v[76:77], v[76:77], v[228:229]
	v_pk_add_f32 v[78:79], v[78:79], v[230:231]
